# v118 with a quarter-step (s_sleep 20) instead of half-step HW wave-slot stagger
# baseline (speedup 1.0000x reference)
.LBB0_209:
	s_not_b32 s2, s5
	s_add_i32 s2, s8, s2
	s_add_i32 s2, s2, s17
	s_ashr_i32 s3, s2, 31
	s_abs_i32 s2, s2
	s_mul_hi_u32 s5, s2, s72
	s_mul_i32 s8, s5, s4
	s_sub_i32 s2, s2, s8
	s_xor_b32 s3, s3, s16
	s_add_i32 s8, s5, 1
	s_sub_i32 s9, s2, s4
	s_cmp_ge_u32 s2, s4
	s_cselect_b32 s5, s8, s5
	s_cselect_b32 s2, s9, s2
	s_add_i32 s8, s5, 1
	s_cmp_ge_u32 s2, s4
	s_cselect_b32 s2, s8, s5
	s_xor_b32 s2, s2, s3
	s_sub_i32 s2, s2, s3
	s_add_i32 s3, s15, s24
	s_not_b32 s4, s23
	s_add_i32 s4, s4, s3
	s_ashr_i32 s3, s4, 31
	s_abs_i32 s4, s4
	s_mul_i32 s1, s4, s1
	s_mul_hi_u32 s0, s4, s0
	s_add_i32 s0, s0, s1
	s_mul_i32 s1, s0, s12
	s_sub_i32 s1, s4, s1
	s_xor_b32 s3, s3, s13
	s_add_i32 s4, s0, 1
	s_sub_i32 s5, s1, s12
	s_cmp_ge_u32 s1, s12
	s_cselect_b32 s0, s4, s0
	s_cselect_b32 s1, s5, s1
	s_add_i32 s4, s0, 1
	s_cmp_ge_u32 s1, s12
	s_cselect_b32 s0, s4, s0
	s_xor_b32 s0, s0, s3
	s_sub_i32 s3, s0, s3
	s_cmp_lt_i32 s22, 0
	s_cselect_b64 s[8:9], -1, 0
	s_and_b64 s[0:1], s[8:9], exec
	s_cselect_b32 s26, s3, s2
	s_not_b32 s0, s14
	s_lshr_b32 s0, s0, 31
	s_add_i32 s26, s26, s0
	s_cmp_lt_i32 s26, 1
	s_cbranch_scc1 .LBB0_476
	s_lshr_b32 s27, s10, 3
	s_cmp_lt_i32 s14, 0
	s_mul_hi_u32 s0, s14, 0x3521cfb3
	s_cselect_b64 s[10:11], -1, 0
	s_sub_i32 s2, s14, s0
	s_lshr_b32 s2, s2, 1
	s_add_i32 s2, s2, s0
	s_lshr_b32 s0, s2, 5
	s_add_i32 s28, s0, 0x80
	s_mul_i32 s0, s0, 53
	v_and_b32_e32 v2, 15, v0
	s_sub_i32 s29, s14, s0
	v_ashrrev_i32_e32 v3, 1, v0
	s_movk_i32 s0, 0xffc0
	v_and_or_b32 v87, v3, s0, v2
	v_lshrrev_b32_e32 v2, 2, v0
	v_and_b32_e32 v2, 12, v2
	v_and_or_b32 v86, v0, 64, v2
	v_and_b32_e32 v0, 64, v0
	v_cmp_ne_u32_e64 s[40:41], 0, v0
	v_or_b32_e32 v0, 16, v86
	v_cmp_gt_u32_e64 s[44:45], 40, v0
	v_or_b32_e32 v0, 32, v86
	v_cmp_gt_u32_e64 s[4:5], 40, v0
	v_cvt_f32_u32_e32 v0, s25
	v_readlane_b32 s2, v249, 52
	s_load_dwordx2 s[12:13], s[6:7], 0x138
	s_load_dwordx2 s[14:15], s[6:7], 0xe0
	s_lshl_b32 s0, s2, 8
	v_rcp_iflag_f32_e32 v0, v0
	s_or_b32 s30, s0, 0xffffc000
	s_sub_i32 s0, 0, s25
	s_mov_b32 s18, s2
	v_mul_f32_e32 v0, 0x4f7ffffe, v0
	v_cvt_u32_f32_e32 v0, v0
	v_readlane_b32 s3, v249, 53
	s_mul_i32 s72, s2, 0xc00
	s_lshl_b32 s31, s2, 14
	v_readfirstlane_b32 s16, v0
	s_mul_i32 s0, s0, s16
	s_mul_hi_u32 s0, s16, s0
	s_lshl_b32 s2, s2, 6
	s_add_i32 s33, s16, s0
	s_mul_i32 s16, s18, 0xd40000
	s_mov_b32 s3, s73
	s_mul_hi_u32 s0, s18, 0xd40000
	s_waitcnt lgkmcnt(0)
	s_add_u32 s34, s14, s16
	s_mov_b32 s1, 0
	v_or_b32_e32 v104, 0xfffff180, v86
	v_cmp_gt_u32_e64 s[42:43], 40, v86
	s_addc_u32 s35, s15, s0
	s_lshl_b64 s[16:17], s[72:73], 2
	s_lshl_b64 s[18:19], s[2:3], 2
	v_lshlrev_b32_e32 v105, 2, v2
	s_mov_b32 s32, 0
	v_readlane_b32 s2, v249, 1
	s_nop 0
	s_cmpk_lg_u32 s2, 0x200
	s_cbranch_scc1 .LBB0_212
	s_getreg_b32 s2, hwreg(HW_REG_HW_ID, 0, 4)
	s_and_b32 s2, s2, 1
	s_cmp_eq_u32 s2, 0
	s_cbranch_scc1 .Lg2_nostag
	s_sleep 20

.LBB0_2352:
	v_and_b32_e32 v2, 15, v0
	v_ashrrev_i32_e32 v3, 1, v0
	s_movk_i32 s8, 0xffc0
	s_waitcnt vmcnt(2)
	v_and_or_b32 v74, v3, s8, v2
	v_lshrrev_b32_e32 v2, 1, v0
	v_lshrrev_b32_e32 v0, 2, v0
	s_and_b32 s17, s2, 7
	v_and_b32_e32 v0, 12, v0
	v_and_or_b32 v75, v2, 32, v0
	v_cvt_f32_ubyte0_e32 v0, s17
	v_rcp_iflag_f32_e32 v0, v0
	s_lshr_b32 s16, s2, 3
	s_cmp_lt_i32 s12, 0
	s_cselect_b64 s[2:3], -1, 0
	v_mul_f32_e32 v0, 0x4f7ffffe, v0
	v_cvt_u32_f32_e32 v0, v0
	s_sub_i32 s8, 0, s17
	s_load_dwordx2 s[4:5], s[0:1], 0x108
	s_load_dwordx2 s[6:7], s[0:1], 0x138
	v_readfirstlane_b32 s9, v0
	s_mul_i32 s8, s8, s9
	s_mul_hi_u32 s8, s9, s8
	s_add_i32 s18, s9, s8
	v_readlane_b32 s8, v249, 52
	v_readlane_b32 s9, v249, 53
	s_mov_b32 s10, s8
	s_mul_i32 s9, s10, 0xb00000
	s_mul_hi_u32 s8, s8, 0xb00000
	s_waitcnt lgkmcnt(0)
	s_add_u32 s19, s4, s9
	s_addc_u32 s20, s5, s8
	s_waitcnt vmcnt(0)
	s_mov_b32 s32, 0
	v_readlane_b32 s30, v249, 1
	s_nop 0
	s_cmpk_lg_u32 s30, 0x200
	s_cbranch_scc1 .LBB0_2354
	s_getreg_b32 s30, hwreg(HW_REG_HW_ID, 0, 4)
	s_and_b32 s30, s30, 1
	s_cmp_eq_u32 s30, 0
	s_cbranch_scc1 .Lf2_nostag
	s_sleep 20
